# attention loops: persistent -m seed block for QK MFMA C operand, running K-tile pointers instead of per-tile 64-bit address chains, drop canonicalising max
# speedup vs baseline: 1.0162x; 1.0162x over previous
; DI int TIDX() { int t = threadIdx.x; asm volatile("" : "+v"(t)); return t; }
; template <int DK, bool MLA>
; DI void attn_item(const h16* __restrict__ Q, const h16* __restrict__ Kp, const h16* __restrict__ Kr, const h16* __restrict__ Vt,
;                   int kbeg, int kend, h16* __restrict__ out, h16* sm) {
;     ...
;   const int tid = TIDX(), lane = tid & 63, w = tid >> 6, r = lane & 31, hh = lane >> 5;
;   h16x8 qf[DK / 16];
;   {
;     const h16* qr = Q + (size_t)(w * 32 + r) * DK + hh * 8;
; #pragma unroll
;     for (int ks = 0; ks < DK / 16; ++ks) qf[ks] = *(const h16x8*)(qr + ks * 16);
;   }
;   f32x16 ot[2];
; #pragma unroll
;   for (int i = 0; i < 16; ++i) { ot[0][i] = 0.f; ot[1][i] = 0.f; }
;   float m = -1000.f, lsum = 0.f;
;   u32x4 rkA[NCH], rvA[2], rkB[NCH], rvB[2];
;     ...
;   const int ntile = (kend - kbeg) >> 6;
;   ATT_GLOAD(rkA, rvA, kbeg)
;   ATT_GLOAD(rkB, rvB, kbeg + 64)
.LBB0_2732:
	s_and_b32 s53, s27, 7
	s_or_b32 s11, s53, s13
	s_mov_b64 s[8:9], -1
	s_andn2_b64 vcc, exec, s[6:7]
	s_mul_i32 s27, s11, 0x1100
	s_cbranch_vccz .LBB0_2744
	v_mov_b32_e32 v12, v203
	s_add_i32 s6, s27, s10
	s_mov_b32 s7, s37
	s_movk_i32 s2, 0xffe0
	v_ashrrev_i32_e32 v0, 1, v12
	s_lshl_b64 s[6:7], s[6:7], 7
	s_waitcnt vmcnt(4)
	v_bfi_b32 v144, s2, v0, v12
	s_add_u32 s8, s21, s6
	s_waitcnt vmcnt(2)
	v_ashrrev_i32_e32 v145, 31, v144
	s_addc_u32 s9, s22, s7
	v_bfe_u32 v13, v12, 5, 1
	v_lshlrev_b64 v[2:3], 7, v[144:145]
	v_lshl_add_u64 v[2:3], s[8:9], 0, v[2:3]
	v_lshlrev_b32_e32 v0, 4, v13
	s_lshr_b32 s6, s53, 2
	v_lshl_add_u64 v[2:3], v[2:3], 0, v[0:1]
	s_or_b32 s6, s6, s14
	global_load_dwordx4 v[80:83], v[2:3], off
	global_load_dwordx4 v[84:87], v[2:3], off offset:32
	global_load_dwordx4 v[88:91], v[2:3], off offset:64
	global_load_dwordx4 v[92:95], v[2:3], off offset:96
	v_ashrrev_i32_e32 v2, 31, v12
	s_mul_i32 s38, s6, 0x88000
	v_lshrrev_b32_e32 v2, 29, v2
	v_add_u32_e32 v10, 0x100, v12
	s_add_u32 s6, s23, s38
	v_add_u32_e32 v8, v12, v2
	v_ashrrev_i32_e32 v2, 31, v10
	s_addc_u32 s7, s24, 0
	v_lshrrev_b32_e32 v2, 29, v2
	s_add_u32 s38, s25, s38
	v_add_u32_e32 v4, v10, v2
	s_addc_u32 s39, s48, 0
	v_ashrrev_i32_e32 v15, 3, v4
	s_or_b32 s9, s26, 64
	v_and_b32_e32 v4, -8, v4
	v_ashrrev_i32_e32 v14, 3, v8
	v_add_u32_e32 v2, s9, v15
	v_sub_u32_e32 v16, v10, v4
	v_and_b32_e32 v8, -8, v8
	s_sub_i32 s8, 0x1100, s26
	v_ashrrev_i32_e32 v3, 31, v2
	v_lshlrev_b32_e32 v4, 3, v16
	v_add_u32_e32 v6, s9, v14
	v_sub_u32_e32 v17, v12, v8
	s_lshr_b32 s8, s8, 6
	v_lshlrev_b64 v[2:3], 7, v[2:3]
	v_ashrrev_i32_e32 v5, 31, v4
	v_ashrrev_i32_e32 v7, 31, v6
	v_lshlrev_b32_e32 v8, 3, v17
	s_lshl_b32 s9, s26, 1
	v_lshl_add_u64 v[2:3], s[6:7], 0, v[2:3]
	v_lshlrev_b64 v[4:5], 1, v[4:5]
	v_lshlrev_b64 v[6:7], 7, v[6:7]
	v_ashrrev_i32_e32 v9, 31, v8
	s_add_u32 s38, s38, s9
	v_lshl_add_u64 v[2:3], v[2:3], 0, v[4:5]
	v_lshl_add_u64 v[6:7], s[6:7], 0, v[6:7]
	v_lshlrev_b64 v[8:9], 1, v[8:9]
	s_addc_u32 s39, s39, 0
	v_lshl_add_u64 v[6:7], v[6:7], 0, v[8:9]
	global_load_dwordx4 v[96:99], v[2:3], off
	global_load_dwordx4 v[100:103], v[6:7], off
	v_ashrrev_i32_e32 v18, 3, v10
	v_mov_b64_e32 v[2:3], s[38:39]
	s_movk_i32 s2, 0x2200
	v_lshlrev_b32_e32 v10, 4, v12
	v_ashrrev_i32_e32 v19, 3, v12
	v_add_u32_e32 v130, s26, v15
	v_mad_i64_i32 v[6:7], s[40:41], v18, s2, v[2:3]
	v_and_b32_e32 v10, 0x70, v10
	v_mov_b32_e32 v11, v1
	v_mad_i64_i32 v[2:3], s[40:41], v19, s2, v[2:3]
	v_add_u32_e32 v128, s26, v14
	v_lshl_add_u64 v[134:135], v[2:3], 0, v[10:11]
	v_lshl_add_u64 v[2:3], s[38:39], 0, v[10:11]
	v_ashrrev_i32_e32 v131, 31, v130
	v_mad_i64_i32 v[136:137], s[38:39], v18, s2, v[2:3]
	v_mad_i64_i32 v[138:139], s[38:39], v19, s2, v[2:3]
	v_lshlrev_b64 v[2:3], 7, v[130:131]
	v_ashrrev_i32_e32 v129, 31, v128
	v_lshl_add_u64 v[132:133], v[6:7], 0, v[10:11]
	v_lshl_add_u64 v[2:3], s[6:7], 0, v[2:3]
	v_lshlrev_b64 v[6:7], 7, v[128:129]
	v_lshl_add_u64 v[2:3], v[2:3], 0, v[4:5]
	v_lshl_add_u64 v[6:7], s[6:7], 0, v[6:7]
	global_load_dwordx4 v[104:107], v[132:133], off offset:128
	global_load_dwordx4 v[108:111], v[134:135], off offset:128
	global_load_dwordx4 v[112:115], v[136:137], off
	global_load_dwordx4 v[116:119], v[138:139], off
	v_lshl_add_u64 v[6:7], v[6:7], 0, v[8:9]
	global_load_dwordx4 v[120:123], v[2:3], off
	global_load_dwordx4 v[124:127], v[6:7], off
	v_and_b32_e32 v2, 31, v12
	v_mul_lo_u32 v3, v14, s28
	v_mul_u32_u24_e32 v2, 0x48, v2
	v_lshl_add_u32 v129, v17, 4, v3
	v_mul_lo_u32 v3, v15, s28
	v_mad_u64_u32 v[140:141], s[38:39], v19, s28, v[10:11]
	v_mad_u64_u32 v[142:143], s[38:39], v18, s28, v[10:11]
	v_lshlrev_b32_e32 v2, 1, v2
	v_mov_b32_e32 v14, v1
	v_mov_b32_e32 v15, v1
	v_lshl_add_u32 v131, v16, 4, v3
	v_lshl_add_u64 v[148:149], s[6:7], 0, v[8:9]
	v_lshl_add_u64 v[150:151], s[6:7], 0, v[4:5]
	v_add_u32_e32 v141, v2, v0
	s_waitcnt vmcnt(13)
	v_lshlrev_b32_e32 v146, 2, v13
	v_lshl_add_u32 v143, v13, 4, v2
	v_mov_b32_e32 v0, v1
	v_mov_b32_e32 v2, v1
	v_mov_b32_e32 v3, v1
	v_mov_b32_e32 v4, v1
	v_mov_b32_e32 v5, v1
	v_mov_b32_e32 v6, v1
	v_mov_b32_e32 v7, v1
	v_mov_b32_e32 v8, v1
	v_mov_b32_e32 v9, v1
	v_mov_b32_e32 v10, v1
	v_mov_b32_e32 v12, v1
	v_mov_b32_e32 v13, v1
	v_mov_b64_e32 v[30:31], v[14:15]
	v_mov_b64_e32 v[46:47], v[14:15]
	s_mov_b32 s9, 3
	s_waitcnt vmcnt(12)
	v_mov_b32_e32 v147, 0xc47a0000
	v_mov_b32_e32 v153, 0
	s_movk_i32 s6, 0xc0
	v_mov_b64_e32 v[28:29], v[12:13]
	v_mov_b64_e32 v[26:27], v[10:11]
	v_mov_b64_e32 v[24:25], v[8:9]
	v_mov_b64_e32 v[22:23], v[6:7]
	v_mov_b64_e32 v[20:21], v[4:5]
	v_mov_b64_e32 v[18:19], v[2:3]
	v_mov_b64_e32 v[16:17], v[0:1]
	v_mov_b64_e32 v[44:45], v[12:13]
	v_mov_b64_e32 v[42:43], v[10:11]
	v_mov_b64_e32 v[40:41], v[8:9]
	v_mov_b64_e32 v[38:39], v[6:7]
	v_mov_b64_e32 v[36:37], v[4:5]
	v_mov_b64_e32 v[34:35], v[2:3]
	v_mov_b64_e32 v[32:33], v[0:1]
	v_mov_b32_e32 v204, 0x447a0000
	v_mov_b32_e32 v205, 0x447a0000
	v_mov_b32_e32 v206, 0x447a0000
	v_mov_b32_e32 v207, 0x447a0000
	v_mov_b32_e32 v208, 0x447a0000
	v_mov_b32_e32 v209, 0x447a0000
	v_mov_b32_e32 v210, 0x447a0000
	v_mov_b32_e32 v211, 0x447a0000
	v_mov_b32_e32 v212, 0x447a0000
	v_mov_b32_e32 v213, 0x447a0000
	v_mov_b32_e32 v214, 0x447a0000
	v_mov_b32_e32 v215, 0x447a0000
	v_mov_b32_e32 v216, 0x447a0000
	v_mov_b32_e32 v217, 0x447a0000
	v_mov_b32_e32 v218, 0x447a0000
	v_mov_b32_e32 v219, 0x447a0000
	s_movk_i32 s40, 0x80
	v_add_u32_e32 v2, s40, v128
	v_ashrrev_i32_e32 v3, 31, v2
	v_add_u32_e32 v4, s40, v130
	v_lshlrev_b64 v[2:3], 7, v[2:3]
	v_ashrrev_i32_e32 v5, 31, v4
	v_lshl_add_u64 v[220:221], v[148:149], 0, v[2:3]
	v_lshlrev_b64 v[4:5], 7, v[4:5]
	v_lshl_add_u64 v[222:223], v[150:151], 0, v[4:5]
	v_mov_b32_e32 v228, 0x2000
	v_mov_b32_e32 v229, 0
	s_branch .LBB0_2735

; #define MFMA(a, b, c) __builtin_amdgcn_mfma_f32_32x32x16_f16((a), (b), (c), 0, 0, 0)
; template <int DK, bool MLA>
; DI void attn_item(const h16* __restrict__ Q, const h16* __restrict__ Kp, const h16* __restrict__ Kr, const h16* __restrict__ Vt,
;                   int kbeg, int kend, h16* __restrict__ out, h16* sm) {
;     ...
;     h16* ksm = sm + (it & 1) * BUF;
;     h16* vsm = ksm + 64 * KS;
; #pragma unroll
;     for (int i = 0; i < NCH; ++i) {
;       const int c = tid + 256 * i, key = c / NKC, part = c % NKC;
;       *(u32x4*)(ksm + key * KS + part * 8) = RK[i];
;     }
; #pragma unroll
;     for (int i = 0; i < 2; ++i) {
;       const int c = tid + 256 * i, dv = c >> 3, kc = c & 7;
;       *(u32x4*)(vsm + dv * 72 + kc * 8) = RV[i];
;     }
;     __syncthreads();
;     if (it + 2 < ntile) ATT_GLOAD(RK, RV, kbeg + (it + 2) * 64)
;     f32x16 st[2];
;     const float negm = -m;
; #pragma unroll
;     for (int i = 0; i < 16; ++i) { st[0][i] = negm; st[1][i] = negm; }
; #pragma unroll
;     for (int ks = 0; ks < DK / 16; ++ks) {
;       h16x8 k0 = *(const h16x8*)(ksm + r * KS + ks * 16 + hh * 8);
;       h16x8 k1 = *(const h16x8*)(ksm + (32 + r) * KS + ks * 16 + hh * 8);
;       st[0] = MFMA(k0, qf[ks], st[0]);
;       st[1] = MFMA(k1, qf[ks], st[1]);
;     }
;     float mx = fmaxf(st[0][0], st[1][0]);
; #pragma unroll
;     for (int i = 1; i < 16; ++i) mx = fmaxf(mx, fmaxf(st[0][i], st[1][i]));
;     mx = x32_max(mx);
;     if (__builtin_amdgcn_ballot_w64(mx > 8.f) != 0) {
;       const float dlt = fmaxf(mx, 0.f);
;       const float alpha = __builtin_amdgcn_exp2f(-dlt);
;       m += dlt;
;       lsum *= alpha;
; #pragma unroll
;       for (int i = 0; i < 16; ++i) { ot[0][i] *= alpha; ot[1][i] *= alpha; st[0][i] -= dlt; st[1][i] -= dlt; }
.LBB0_2735:
	s_add_i32 s38, s9, -1
	s_cmp_ge_u32 s38, s8
	s_waitcnt vmcnt(0)
	ds_write_b128 v129, v[124:127]
	ds_write_b128 v131, v[120:123]
	ds_write_b128 v140, v[116:119] offset:9216
	ds_write_b128 v142, v[112:115] offset:9216
	s_waitcnt lgkmcnt(0)
	s_barrier
	s_cbranch_scc1 .LBB0_2737
	s_sub_i32 s40, s6, 64
	s_ashr_i32 s41, s40, 31
	s_lshl_b64 s[40:41], s[40:41], 1
	global_load_dwordx4 v[124:127], v[220:221], off
	global_load_dwordx4 v[120:123], v[222:223], off
	v_lshl_add_u64 v[2:3], v[138:139], 0, s[40:41]
	v_lshl_add_u64 v[4:5], v[136:137], 0, s[40:41]
	global_load_dwordx4 v[116:119], v[2:3], off
	global_load_dwordx4 v[112:115], v[4:5], off
	v_lshl_add_u64 v[220:221], v[220:221], 0, v[228:229]
	v_lshl_add_u64 v[222:223], v[222:223], 0, v[228:229]
.LBB0_2737:
	ds_read_b128 v[2:5], v141
	s_waitcnt lgkmcnt(0)
	s_nop 0
	v_mfma_f32_32x32x16_f16 v[64:79], v[2:5], v[80:83], v[204:219]
	ds_read_b128 v[2:5], v141 offset:4608
	s_waitcnt lgkmcnt(0)
	v_mfma_f32_32x32x16_f16 v[48:63], v[2:5], v[80:83], v[204:219]
	ds_read_b128 v[2:5], v141 offset:32
	s_waitcnt lgkmcnt(0)
	v_mfma_f32_32x32x16_f16 v[64:79], v[2:5], v[84:87], v[64:79]
	ds_read_b128 v[2:5], v141 offset:4640
	s_waitcnt lgkmcnt(0)
	v_mfma_f32_32x32x16_f16 v[48:63], v[2:5], v[84:87], v[48:63]
	ds_read_b128 v[2:5], v141 offset:64
	s_waitcnt lgkmcnt(0)
	v_mfma_f32_32x32x16_f16 v[64:79], v[2:5], v[88:91], v[64:79]
	ds_read_b128 v[2:5], v141 offset:4672
	s_waitcnt lgkmcnt(0)
	v_mfma_f32_32x32x16_f16 v[48:63], v[2:5], v[88:91], v[48:63]
	ds_read_b128 v[2:5], v141 offset:4704
	s_waitcnt lgkmcnt(0)
	v_mfma_f32_32x32x16_f16 v[48:63], v[2:5], v[92:95], v[48:63]
	ds_read_b128 v[2:5], v141 offset:96
	s_waitcnt lgkmcnt(0)
	v_mfma_f32_32x32x16_f16 v[64:79], v[2:5], v[92:95], v[64:79]
	s_nop 8
	v_max3_f32 v0, v48, v49, v50
	v_max3_f32 v2, v51, v52, v53
	v_max3_f32 v3, v54, v55, v56
	v_max3_f32 v4, v57, v58, v59
	v_max3_f32 v0, v0, v60, v61
	v_max3_f32 v2, v2, v62, v63
	v_max3_f32 v3, v3, v64, v65
	v_max3_f32 v4, v4, v66, v67
	v_max3_f32 v0, v0, v68, v69
	v_max3_f32 v2, v2, v70, v71
	v_max3_f32 v3, v3, v72, v73
	v_max3_f32 v4, v4, v74, v75
	v_max3_f32 v0, v0, v76, v77
	v_max3_f32 v2, v2, v78, v79
	v_max3_f32 v0, v0, v2, v3
	v_max_f32_e32 v0, v0, v4
	v_mov_b32_e32 v2, v0
	s_nop 1
	v_permlane32_swap_b32_e32 v0, v2
	v_max_f32_e32 v0, v0, v2
	v_cmp_lt_f32_e32 vcc, s79, v0
	s_cbranch_vccz .LBB0_2739
	v_max_f32_e32 v0, v0, v0
	v_max_f32_e32 v0, 0, v0
	v_exp_f32_e64 v2, -v0
	v_add_f32_e32 v147, v147, v0
	v_xor_b32_e32 v204, 0x80000000, v147
	v_mov_b32_e32 v205, v204
	v_mov_b32_e32 v206, v204
	v_mov_b32_e32 v207, v204
	v_mov_b32_e32 v208, v204
	v_mov_b32_e32 v209, v204
	v_mov_b32_e32 v210, v204
	v_mov_b32_e32 v211, v204
	v_mov_b32_e32 v212, v204
	v_mov_b32_e32 v213, v204
	v_mov_b32_e32 v214, v204
	v_mov_b32_e32 v215, v204
	v_mov_b32_e32 v216, v204
	v_mov_b32_e32 v217, v204
	v_mov_b32_e32 v218, v204
	v_mov_b32_e32 v219, v204
	v_pk_add_f32 v[64:65], v[64:65], v[0:1] op_sel_hi:[1,0] neg_lo:[0,1] neg_hi:[0,1]
	v_pk_add_f32 v[48:49], v[48:49], v[0:1] op_sel_hi:[1,0] neg_lo:[0,1] neg_hi:[0,1]
	v_mul_f32_e32 v153, v153, v2
	v_pk_add_f32 v[66:67], v[66:67], v[0:1] op_sel_hi:[1,0] neg_lo:[0,1] neg_hi:[0,1]
	v_pk_add_f32 v[50:51], v[50:51], v[0:1] op_sel_hi:[1,0] neg_lo:[0,1] neg_hi:[0,1]
	v_pk_add_f32 v[68:69], v[68:69], v[0:1] op_sel_hi:[1,0] neg_lo:[0,1] neg_hi:[0,1]
	v_pk_add_f32 v[52:53], v[52:53], v[0:1] op_sel_hi:[1,0] neg_lo:[0,1] neg_hi:[0,1]
	v_pk_add_f32 v[70:71], v[70:71], v[0:1] op_sel_hi:[1,0] neg_lo:[0,1] neg_hi:[0,1]
	v_pk_add_f32 v[54:55], v[54:55], v[0:1] op_sel_hi:[1,0] neg_lo:[0,1] neg_hi:[0,1]
	v_pk_add_f32 v[72:73], v[72:73], v[0:1] op_sel_hi:[1,0] neg_lo:[0,1] neg_hi:[0,1]
	v_pk_add_f32 v[56:57], v[56:57], v[0:1] op_sel_hi:[1,0] neg_lo:[0,1] neg_hi:[0,1]
	v_pk_add_f32 v[74:75], v[74:75], v[0:1] op_sel_hi:[1,0] neg_lo:[0,1] neg_hi:[0,1]
	v_pk_add_f32 v[58:59], v[58:59], v[0:1] op_sel_hi:[1,0] neg_lo:[0,1] neg_hi:[0,1]
	v_pk_add_f32 v[76:77], v[76:77], v[0:1] op_sel_hi:[1,0] neg_lo:[0,1] neg_hi:[0,1]
	v_pk_add_f32 v[60:61], v[60:61], v[0:1] op_sel_hi:[1,0] neg_lo:[0,1] neg_hi:[0,1]
	v_pk_mul_f32 v[46:47], v[46:47], v[2:3] op_sel_hi:[1,0]
	v_pk_mul_f32 v[44:45], v[44:45], v[2:3] op_sel_hi:[1,0]
	v_pk_mul_f32 v[42:43], v[42:43], v[2:3] op_sel_hi:[1,0]
	v_pk_mul_f32 v[40:41], v[40:41], v[2:3] op_sel_hi:[1,0]
	v_pk_mul_f32 v[38:39], v[38:39], v[2:3] op_sel_hi:[1,0]
	v_pk_mul_f32 v[36:37], v[36:37], v[2:3] op_sel_hi:[1,0]
	v_pk_mul_f32 v[34:35], v[34:35], v[2:3] op_sel_hi:[1,0]
	v_pk_mul_f32 v[32:33], v[32:33], v[2:3] op_sel_hi:[1,0]
	v_pk_mul_f32 v[30:31], v[30:31], v[2:3] op_sel_hi:[1,0]
	v_pk_mul_f32 v[28:29], v[28:29], v[2:3] op_sel_hi:[1,0]
	v_pk_mul_f32 v[26:27], v[26:27], v[2:3] op_sel_hi:[1,0]
	v_pk_mul_f32 v[24:25], v[24:25], v[2:3] op_sel_hi:[1,0]
	v_pk_mul_f32 v[22:23], v[22:23], v[2:3] op_sel_hi:[1,0]
	v_pk_mul_f32 v[20:21], v[20:21], v[2:3] op_sel_hi:[1,0]
	v_pk_mul_f32 v[18:19], v[18:19], v[2:3] op_sel_hi:[1,0]
	v_pk_mul_f32 v[16:17], v[16:17], v[2:3] op_sel_hi:[1,0]
	v_pk_add_f32 v[78:79], v[78:79], v[0:1] op_sel_hi:[1,0] neg_lo:[0,1] neg_hi:[0,1]
	v_pk_add_f32 v[62:63], v[62:63], v[0:1] op_sel_hi:[1,0] neg_lo:[0,1] neg_hi:[0,1]
; #define MFMA(a, b, c) __builtin_amdgcn_mfma_f32_32x32x16_f16((a), (b), (c), 0, 0, 0)
; template <int DK, bool MLA>
; DI void attn_item(const h16* __restrict__ Q, const h16* __restrict__ Kp, const h16* __restrict__ Kr, const h16* __restrict__ Vt,
;                   int kbeg, int kend, h16* __restrict__ out, h16* sm) {
;     ...
;     h16* ksm = sm + (it & 1) * BUF;
;     h16* vsm = ksm + 64 * KS;
; #pragma unroll
;     for (int i = 0; i < NCH; ++i) {
;       const int c = tid + 256 * i, key = c / NKC, part = c % NKC;
;       *(u32x4*)(ksm + key * KS + part * 8) = RK[i];
;     }
; #pragma unroll
;     for (int i = 0; i < 2; ++i) {
;       const int c = tid + 256 * i, dv = c >> 3, kc = c & 7;
;       *(u32x4*)(vsm + dv * 72 + kc * 8) = RV[i];
;     }
;     __syncthreads();
;     if (it + 2 < ntile) ATT_GLOAD(RK, RV, kbeg + (it + 2) * 64)
;     ...
;     float ps = 0.f;
; #pragma unroll
;     for (int i = 0; i < 16; ++i) {
;       st[0][i] = __builtin_amdgcn_exp2f(st[0][i]);
;       st[1][i] = __builtin_amdgcn_exp2f(st[1][i]);
;       ps += st[0][i] + st[1][i];
;     }
;     lsum += ps;
; #pragma unroll
;     for (int s4 = 0; s4 < 4; ++s4) {
;       const int kt2 = s4 >> 1, hf = s4 & 1;
;       h16x8 pb;
; #pragma unroll
;       for (int j = 0; j < 8; ++j) pb[j] = (h16)st[kt2][8 * hf + j];
;       const int kb = kt2 * 32 + 16 * hf;
; #pragma unroll
;       for (int dt = 0; dt < 2; ++dt) {
;         const h16* vp = vsm + (dt * 32 + r) * 72 + kb + 4 * hh;
;         h16x4 lo = *(const h16x4*)vp, hi = *(const h16x4*)(vp + 8);
;         h16x8 va = __builtin_shufflevector(lo, hi, 0, 1, 2, 3, 4, 5, 6, 7);
;         ot[dt] = MFMA(va, pb, ot[dt]);
;       }
;     }
.LBB0_2739:
	v_exp_f32_e32 v166, v64
	v_exp_f32_e32 v13, v65
	v_exp_f32_e32 v15, v66
	v_exp_f32_e32 v152, v67
	v_exp_f32_e32 v156, v68
	v_exp_f32_e32 v157, v69
	v_exp_f32_e32 v168, v70
	v_exp_f32_e32 v160, v71
	v_exp_f32_e32 v12, v60
	v_add_u32_e32 v60, 0x2000, v143
	v_exp_f32_e32 v158, v52
	v_exp_f32_e32 v159, v53
	v_exp_f32_e32 v169, v54
	v_exp_f32_e32 v163, v55
	v_exp_f32_e32 v164, v56
	v_exp_f32_e32 v165, v57
	v_exp_f32_e32 v10, v58
	v_exp_f32_e32 v11, v59
	ds_read_b128 v[52:55], v60 offset:1024
	ds_read_b128 v[56:59], v60 offset:1056
	v_exp_f32_e32 v167, v48
	v_exp_f32_e32 v14, v49
	v_exp_f32_e32 v154, v50
	v_exp_f32_e32 v155, v51
	v_exp_f32_e32 v4, v61
	v_cvt_pk_f16_f32 v51, v168, v160
	v_cvt_pk_f16_f32 v50, v156, v157
	v_cvt_pk_f16_f32 v49, v15, v152
	v_cvt_pk_f16_f32 v48, v166, v13
	v_add_u32_e32 v61, 0x3000, v143
	v_exp_f32_e32 v161, v72
	s_waitcnt lgkmcnt(1)
	v_mfma_f32_32x32x16_f16 v[32:47], v[52:55], v[48:51], v[32:47]
	ds_read_b128 v[52:55], v61 offset:1536
	v_exp_f32_e32 v162, v73
	v_exp_f32_e32 v7, v74
	v_exp_f32_e32 v8, v75
	v_exp_f32_e32 v9, v76
	v_exp_f32_e32 v0, v77
	v_exp_f32_e32 v2, v78
	s_waitcnt lgkmcnt(0)
	v_mfma_f32_32x32x16_f16 v[16:31], v[52:55], v[48:51], v[16:31]
	ds_read_b128 v[52:55], v61 offset:1568
	v_exp_f32_e32 v3, v79
	v_cvt_pk_f16_f32 v50, v9, v0
	v_cvt_pk_f16_f32 v49, v7, v8
	v_cvt_pk_f16_f32 v48, v161, v162
	v_cvt_pk_f16_f32 v51, v2, v3
	v_exp_f32_e32 v5, v62
	v_exp_f32_e32 v6, v63
	s_waitcnt lgkmcnt(0)
	v_mfma_f32_32x32x16_f16 v[16:31], v[52:55], v[48:51], v[16:31]
	ds_read_b128 v[52:55], v60 offset:1088
	s_cmp_ge_u32 s9, s8
	v_mfma_f32_32x32x16_f16 v[32:47], v[56:59], v[48:51], v[32:47]
	v_cvt_pk_f16_f32 v51, v169, v163
	v_cvt_pk_f16_f32 v50, v158, v159
	v_cvt_pk_f16_f32 v49, v154, v155
	v_cvt_pk_f16_f32 v48, v167, v14
	s_waitcnt lgkmcnt(0)
	s_nop 0
	v_mfma_f32_32x32x16_f16 v[32:47], v[52:55], v[48:51], v[32:47]
	ds_read_b128 v[52:55], v61 offset:1600
	s_waitcnt lgkmcnt(0)
	v_mfma_f32_32x32x16_f16 v[16:31], v[52:55], v[48:51], v[16:31]
	ds_read_b128 v[52:55], v60 offset:1120
	v_cvt_pk_f16_f32 v51, v5, v6
	v_cvt_pk_f16_f32 v50, v12, v4
	v_cvt_pk_f16_f32 v49, v10, v11
	v_cvt_pk_f16_f32 v48, v164, v165
	s_waitcnt lgkmcnt(0)
	s_nop 0
	v_mfma_f32_32x32x16_f16 v[32:47], v[52:55], v[48:51], v[32:47]
	ds_read_b128 v[52:55], v61 offset:1632
	ds_write_b128 v129, v[100:103] offset:18432
	ds_write_b128 v131, v[96:99] offset:18432
	ds_write_b128 v140, v[108:111] offset:27648
	ds_write_b128 v142, v[104:107] offset:27648
	s_waitcnt lgkmcnt(0)
	s_barrier
	v_mfma_f32_32x32x16_f16 v[16:31], v[52:55], v[48:51], v[16:31]
	s_cbranch_scc1 .LBB0_2741
	s_ashr_i32 s7, s6, 31
	s_lshl_b64 s[40:41], s[6:7], 1
	global_load_dwordx4 v[100:103], v[220:221], off
	global_load_dwordx4 v[96:99], v[222:223], off
	v_lshl_add_u64 v[48:49], v[134:135], 0, s[40:41]
	v_lshl_add_u64 v[50:51], v[132:133], 0, s[40:41]
	global_load_dwordx4 v[108:111], v[48:49], off
	global_load_dwordx4 v[104:107], v[50:51], off
	v_lshl_add_u64 v[220:221], v[220:221], 0, v[228:229]
	v_lshl_add_u64 v[222:223], v[222:223], 0, v[228:229]
; #define MFMA(a, b, c) __builtin_amdgcn_mfma_f32_32x32x16_f16((a), (b), (c), 0, 0, 0)
; template <int DK, bool MLA>
; DI void attn_item(const h16* __restrict__ Q, const h16* __restrict__ Kp, const h16* __restrict__ Kr, const h16* __restrict__ Vt,
;                   int kbeg, int kend, h16* __restrict__ out, h16* sm) {
;     ...
;     f32x16 st[2];
;     const float negm = -m;
; #pragma unroll
;     for (int i = 0; i < 16; ++i) { st[0][i] = negm; st[1][i] = negm; }
; #pragma unroll
;     for (int ks = 0; ks < DK / 16; ++ks) {
;       h16x8 k0 = *(const h16x8*)(ksm + r * KS + ks * 16 + hh * 8);
;       h16x8 k1 = *(const h16x8*)(ksm + (32 + r) * KS + ks * 16 + hh * 8);
;       st[0] = MFMA(k0, qf[ks], st[0]);
;       st[1] = MFMA(k1, qf[ks], st[1]);
;     }
;     float mx = fmaxf(st[0][0], st[1][0]);
; #pragma unroll
;     for (int i = 1; i < 16; ++i) mx = fmaxf(mx, fmaxf(st[0][i], st[1][i]));
;     mx = x32_max(mx);
;     if (__builtin_amdgcn_ballot_w64(mx > 8.f) != 0) {
;       const float dlt = fmaxf(mx, 0.f);
;       const float alpha = __builtin_amdgcn_exp2f(-dlt);
;       m += dlt;
;       lsum *= alpha;
; #pragma unroll
;       for (int i = 0; i < 16; ++i) { ot[0][i] *= alpha; ot[1][i] *= alpha; st[0][i] -= dlt; st[1][i] -= dlt; }
;     }
;     float ps = 0.f;
; #pragma unroll
;     for (int i = 0; i < 16; ++i) {
;       st[0][i] = __builtin_amdgcn_exp2f(st[0][i]);
;       st[1][i] = __builtin_amdgcn_exp2f(st[1][i]);
;       ps += st[0][i] + st[1][i];
;     }
;     lsum += ps;
.LBB0_2741:
	ds_read_b128 v[170:173], v141 offset:18432
	v_add_f32_e32 v166, v167, v166
	v_add_f32_e32 v166, 0, v166
	v_add_f32_e32 v13, v14, v13
	v_add_f32_e32 v13, v13, v166
	v_add_f32_e32 v14, v154, v15
	v_add_f32_e32 v13, v14, v13
	v_add_f32_e32 v14, v155, v152
	v_add_f32_e32 v13, v14, v13
	v_add_f32_e32 v14, v158, v156
	v_add_f32_e32 v13, v14, v13
	v_add_f32_e32 v14, v159, v157
	v_add_f32_e32 v13, v14, v13
	v_add_f32_e32 v14, v169, v168
	v_add_f32_e32 v13, v14, v13
	v_add_f32_e32 v14, v163, v160
	v_add_f32_e32 v13, v14, v13
	v_add_f32_e32 v14, v164, v161
	ds_read_b128 v[158:161], v141 offset:18528
	s_waitcnt lgkmcnt(1)
	v_mfma_f32_32x32x16_f16 v[64:79], v[170:173], v[80:83], v[204:219]
	ds_read_b128 v[170:173], v141 offset:23040
	v_add_f32_e32 v13, v14, v13
	v_add_f32_e32 v14, v165, v162
	v_add_f32_e32 v13, v14, v13
	v_add_f32_e32 v7, v10, v7
	v_add_f32_e32 v7, v7, v13
	v_add_f32_e32 v8, v11, v8
	v_add_f32_e32 v7, v8, v7
	v_add_f32_e32 v8, v12, v9
	v_add_f32_e32 v7, v8, v7
	ds_read_b128 v[8:11], v141 offset:23136
	s_waitcnt lgkmcnt(1)
	v_mfma_f32_32x32x16_f16 v[48:63], v[170:173], v[80:83], v[204:219]
	ds_read_b128 v[170:173], v141 offset:18464
	ds_read_b128 v[174:177], v141 offset:23072
	ds_read_b128 v[154:157], v141 offset:23104
	v_add_f32_e32 v0, v4, v0
	v_add_f32_e32 v0, v0, v7
	v_add_f32_e32 v2, v5, v2
	v_add_f32_e32 v0, v2, v0
	s_waitcnt lgkmcnt(2)
	v_mfma_f32_32x32x16_f16 v[64:79], v[170:173], v[84:87], v[64:79]
	ds_read_b128 v[170:173], v141 offset:18496
	v_add_f32_e32 v2, v6, v3
	v_add_f32_e32 v0, v2, v0
	v_add_f32_e32 v0, v153, v0
	s_waitcnt lgkmcnt(2)
	v_mfma_f32_32x32x16_f16 v[48:63], v[174:177], v[84:87], v[48:63]
	s_waitcnt lgkmcnt(0)
	v_mfma_f32_32x32x16_f16 v[64:79], v[170:173], v[88:91], v[64:79]
	v_mfma_f32_32x32x16_f16 v[48:63], v[154:157], v[88:91], v[48:63]
	v_mfma_f32_32x32x16_f16 v[64:79], v[158:161], v[92:95], v[64:79]
	v_mfma_f32_32x32x16_f16 v[48:63], v[8:11], v[92:95], v[48:63]
	s_nop 10
	v_max3_f32 v2, v64, v65, v66
	v_max3_f32 v3, v67, v68, v69
	v_max3_f32 v4, v70, v71, v72
	v_max3_f32 v5, v73, v74, v75
	v_max3_f32 v2, v2, v76, v77
	v_max3_f32 v3, v3, v78, v79
	v_max3_f32 v4, v4, v48, v49
	v_max3_f32 v5, v5, v50, v51
	v_max3_f32 v2, v2, v52, v53
	v_max3_f32 v3, v3, v54, v55
	v_max3_f32 v4, v4, v56, v57
	v_max3_f32 v5, v5, v58, v59
	v_max3_f32 v2, v2, v60, v61
	v_max3_f32 v3, v3, v62, v63
	v_max3_f32 v2, v2, v3, v4
	v_max_f32_e32 v2, v2, v5
	v_mov_b32_e32 v3, v2
	s_nop 1
	v_permlane32_swap_b32_e32 v2, v3
	v_max_f32_e32 v2, v2, v3
	v_cmp_lt_f32_e32 vcc, s79, v2
	s_cbranch_vccz .LBB0_2734
	v_max_f32_e32 v2, v2, v2
	v_max_f32_e32 v2, 0, v2
	v_exp_f32_e64 v4, -v2
	v_add_f32_e32 v147, v147, v2
	v_xor_b32_e32 v204, 0x80000000, v147
	v_mov_b32_e32 v205, v204
	v_mov_b32_e32 v206, v204
	v_mov_b32_e32 v207, v204
	v_mov_b32_e32 v208, v204
	v_mov_b32_e32 v209, v204
	v_mov_b32_e32 v210, v204
	v_mov_b32_e32 v211, v204
	v_mov_b32_e32 v212, v204
	v_mov_b32_e32 v213, v204
	v_mov_b32_e32 v214, v204
	v_mov_b32_e32 v215, v204
	v_mov_b32_e32 v216, v204
	v_mov_b32_e32 v217, v204
	v_mov_b32_e32 v218, v204
	v_mov_b32_e32 v219, v204
	v_pk_add_f32 v[64:65], v[64:65], v[2:3] op_sel_hi:[1,0] neg_lo:[0,1] neg_hi:[0,1]
	v_pk_add_f32 v[48:49], v[48:49], v[2:3] op_sel_hi:[1,0] neg_lo:[0,1] neg_hi:[0,1]
	v_mul_f32_e32 v0, v0, v4
	v_pk_add_f32 v[66:67], v[66:67], v[2:3] op_sel_hi:[1,0] neg_lo:[0,1] neg_hi:[0,1]
	v_pk_add_f32 v[50:51], v[50:51], v[2:3] op_sel_hi:[1,0] neg_lo:[0,1] neg_hi:[0,1]
	v_pk_add_f32 v[68:69], v[68:69], v[2:3] op_sel_hi:[1,0] neg_lo:[0,1] neg_hi:[0,1]
	v_pk_add_f32 v[52:53], v[52:53], v[2:3] op_sel_hi:[1,0] neg_lo:[0,1] neg_hi:[0,1]
	v_pk_add_f32 v[70:71], v[70:71], v[2:3] op_sel_hi:[1,0] neg_lo:[0,1] neg_hi:[0,1]
	v_pk_add_f32 v[54:55], v[54:55], v[2:3] op_sel_hi:[1,0] neg_lo:[0,1] neg_hi:[0,1]
	v_pk_add_f32 v[72:73], v[72:73], v[2:3] op_sel_hi:[1,0] neg_lo:[0,1] neg_hi:[0,1]
	v_pk_add_f32 v[56:57], v[56:57], v[2:3] op_sel_hi:[1,0] neg_lo:[0,1] neg_hi:[0,1]
	v_pk_add_f32 v[74:75], v[74:75], v[2:3] op_sel_hi:[1,0] neg_lo:[0,1] neg_hi:[0,1]
	v_pk_add_f32 v[58:59], v[58:59], v[2:3] op_sel_hi:[1,0] neg_lo:[0,1] neg_hi:[0,1]
	v_pk_add_f32 v[76:77], v[76:77], v[2:3] op_sel_hi:[1,0] neg_lo:[0,1] neg_hi:[0,1]
	v_pk_add_f32 v[60:61], v[60:61], v[2:3] op_sel_hi:[1,0] neg_lo:[0,1] neg_hi:[0,1]
	v_pk_mul_f32 v[46:47], v[46:47], v[4:5] op_sel_hi:[1,0]
	v_pk_mul_f32 v[44:45], v[44:45], v[4:5] op_sel_hi:[1,0]
	v_pk_mul_f32 v[42:43], v[42:43], v[4:5] op_sel_hi:[1,0]
	v_pk_mul_f32 v[40:41], v[40:41], v[4:5] op_sel_hi:[1,0]
	v_pk_mul_f32 v[38:39], v[38:39], v[4:5] op_sel_hi:[1,0]
	v_pk_mul_f32 v[36:37], v[36:37], v[4:5] op_sel_hi:[1,0]
	v_pk_mul_f32 v[34:35], v[34:35], v[4:5] op_sel_hi:[1,0]
	v_pk_mul_f32 v[32:33], v[32:33], v[4:5] op_sel_hi:[1,0]
	v_pk_mul_f32 v[30:31], v[30:31], v[4:5] op_sel_hi:[1,0]
	v_pk_mul_f32 v[28:29], v[28:29], v[4:5] op_sel_hi:[1,0]
	v_pk_mul_f32 v[26:27], v[26:27], v[4:5] op_sel_hi:[1,0]
	v_pk_mul_f32 v[24:25], v[24:25], v[4:5] op_sel_hi:[1,0]
	v_pk_mul_f32 v[22:23], v[22:23], v[4:5] op_sel_hi:[1,0]
	v_pk_mul_f32 v[20:21], v[20:21], v[4:5] op_sel_hi:[1,0]
	v_pk_mul_f32 v[18:19], v[18:19], v[4:5] op_sel_hi:[1,0]
	v_pk_mul_f32 v[16:17], v[16:17], v[4:5] op_sel_hi:[1,0]
	v_pk_add_f32 v[78:79], v[78:79], v[2:3] op_sel_hi:[1,0] neg_lo:[0,1] neg_hi:[0,1]
	v_pk_add_f32 v[62:63], v[62:63], v[2:3] op_sel_hi:[1,0] neg_lo:[0,1] neg_hi:[0,1]
	s_branch .LBB0_2734

; DI int TIDX() { int t = threadIdx.x; asm volatile("" : "+v"(t)); return t; }
; template <int DK, bool MLA>
; DI void attn_item(const h16* __restrict__ Q, const h16* __restrict__ Kp, const h16* __restrict__ Kr, const h16* __restrict__ Vt,
;                   int kbeg, int kend, h16* __restrict__ out, h16* sm) {
;     ...
;   const int tid = TIDX(), lane = tid & 63, w = tid >> 6, r = lane & 31, hh = lane >> 5;
;   h16x8 qf[DK / 16];
;   {
;     const h16* qr = Q + (size_t)(w * 32 + r) * DK + hh * 8;
; #pragma unroll
;     for (int ks = 0; ks < DK / 16; ++ks) qf[ks] = *(const h16x8*)(qr + ks * 16);
;   }
;   f32x16 ot[2];
; #pragma unroll
;   for (int i = 0; i < 16; ++i) { ot[0][i] = 0.f; ot[1][i] = 0.f; }
;   float m = -1000.f, lsum = 0.f;
;   u32x4 rkA[NCH], rvA[2], rkB[NCH], rvB[2];
;     ...
;   const int ntile = (kend - kbeg) >> 6;
;   ATT_GLOAD(rkA, rvA, kbeg)
;   ATT_GLOAD(rkB, rvB, kbeg + 64)
.LBB0_2744:
	s_and_b64 vcc, exec, s[8:9]
	s_cbranch_vccz .LBB0_2721
	s_add_u32 s6, s27, s10
	s_addc_u32 s7, 0, 0
	s_mulk_i32 s7, 0xc0
	s_mul_hi_u32 s8, s6, 0xc0
	s_add_i32 s8, s8, s7
	s_mulk_i32 s6, 0xc0
	s_add_u32 s6, s15, s6
	v_mov_b32_e32 v17, v203
	s_addc_u32 s7, s16, s8
	s_movk_i32 s2, 0xffe0
	v_ashrrev_i32_e32 v0, 1, v17
	v_bfe_u32 v16, v17, 5, 1
	s_waitcnt vmcnt(4)
	v_bfi_b32 v144, s2, v0, v17
	v_mov_b64_e32 v[2:3], s[6:7]
	v_mad_i64_i32 v[2:3], s[6:7], v144, s29, v[2:3]
	v_lshlrev_b32_e32 v0, 4, v16
	v_lshl_add_u64 v[2:3], v[2:3], 0, v[0:1]
	global_load_dwordx4 v[80:83], v[2:3], off
	global_load_dwordx4 v[84:87], v[2:3], off offset:32
	global_load_dwordx4 v[88:91], v[2:3], off offset:64
	global_load_dwordx4 v[92:95], v[2:3], off offset:96
	global_load_dwordx4 v[96:99], v[2:3], off offset:128
	global_load_dwordx4 v[100:103], v[2:3], off offset:160
	s_mov_b32 s2, 0x2aaaaaab
	v_mul_hi_i32 v0, v17, s2
	v_lshrrev_b32_e32 v2, 31, v0
	v_ashrrev_i32_e32 v0, 1, v0
	v_add_u32_e32 v18, v0, v2
	s_mul_i32 s10, s11, 0x88000
	v_mul_lo_u32 v0, v18, 12
	s_add_u32 s6, s17, s10
	v_sub_u32_e32 v0, v17, v0
	v_add_u32_e32 v148, s26, v18
	s_addc_u32 s7, s18, 0
	v_cmp_gt_i32_e64 s[38:39], 8, v0
	v_cmp_lt_i32_e32 vcc, 7, v0
	v_ashrrev_i32_e32 v149, 31, v148
	v_lshlrev_b32_e32 v2, 3, v0
	s_and_saveexec_b64 s[8:9], vcc
	s_xor_b64 s[8:9], exec, s[8:9]
	v_lshlrev_b64 v[4:5], 6, v[148:149]
	v_lshl_add_u64 v[4:5], s[4:5], 0, v[4:5]
	v_mov_b32_e32 v3, v1
	v_lshl_add_u64 v[4:5], v[2:3], 1, v[4:5]
	v_lshl_add_u64 v[4:5], v[4:5], 0, s[74:75]
	s_or_saveexec_b64 s[8:9], s[8:9]
	v_ashrrev_i32_e32 v3, 31, v2
	s_xor_b64 exec, exec, s[8:9]
	v_lshlrev_b64 v[4:5], 7, v[148:149]
	v_lshl_add_u64 v[4:5], s[6:7], 0, v[4:5]
	v_lshl_add_u64 v[4:5], v[2:3], 1, v[4:5]
	s_or_b64 exec, exec, s[8:9]
	global_load_dwordx4 v[104:107], v[4:5], off
	v_add_u32_e32 v10, 0x100, v17
	v_mul_hi_i32 v0, v10, s2
	v_lshrrev_b32_e32 v4, 31, v0
	v_ashrrev_i32_e32 v0, 1, v0
	v_add_u32_e32 v19, v0, v4
	v_mul_lo_u32 v0, v19, 12
	v_sub_u32_e32 v0, v10, v0
	s_waitcnt vmcnt(10)
	v_add_u32_e32 v150, s26, v19
	v_cmp_gt_i32_e64 s[40:41], 8, v0
	v_cmp_lt_i32_e64 s[44:45], 7, v0
	v_ashrrev_i32_e32 v151, 31, v150
	v_lshlrev_b32_e32 v4, 3, v0
	s_and_saveexec_b64 s[8:9], s[44:45]
	s_xor_b64 s[8:9], exec, s[8:9]
	v_lshlrev_b64 v[6:7], 6, v[150:151]
	v_lshl_add_u64 v[6:7], s[4:5], 0, v[6:7]
	v_mov_b32_e32 v5, v1
	v_lshl_add_u64 v[6:7], v[4:5], 1, v[6:7]
	v_lshl_add_u64 v[6:7], v[6:7], 0, s[74:75]
	s_or_saveexec_b64 s[8:9], s[8:9]
	v_ashrrev_i32_e32 v5, 31, v4
	s_xor_b64 exec, exec, s[8:9]
	v_lshlrev_b64 v[6:7], 7, v[150:151]
	v_lshl_add_u64 v[6:7], s[6:7], 0, v[6:7]
	v_lshl_add_u64 v[6:7], v[4:5], 1, v[6:7]
	s_or_b64 exec, exec, s[8:9]
	global_load_dwordx4 v[108:111], v[6:7], off
	v_add_u32_e32 v0, 0x200, v17
	v_mul_hi_i32 v6, v0, s2
	v_lshrrev_b32_e32 v7, 31, v6
	v_ashrrev_i32_e32 v6, 1, v6
	v_add_u32_e32 v20, v6, v7
	v_mul_lo_u32 v6, v20, 12
	v_sub_u32_e32 v0, v0, v6
	v_add_u32_e32 v152, s26, v20
	v_cmp_gt_i32_e64 s[42:43], 8, v0
	v_cmp_lt_i32_e64 s[46:47], 7, v0
	v_ashrrev_i32_e32 v153, 31, v152
	v_lshlrev_b32_e32 v0, 3, v0
	s_and_saveexec_b64 s[8:9], s[46:47]
	s_xor_b64 s[8:9], exec, s[8:9]
	v_lshlrev_b64 v[6:7], 6, v[152:153]
	v_lshl_add_u64 v[6:7], s[4:5], 0, v[6:7]
	v_lshl_add_u64 v[6:7], v[0:1], 1, v[6:7]
	v_lshl_add_u64 v[6:7], v[6:7], 0, s[74:75]
	s_or_saveexec_b64 s[8:9], s[8:9]
	v_ashrrev_i32_e32 v9, 31, v0
	s_xor_b64 exec, exec, s[8:9]
	v_lshlrev_b64 v[6:7], 7, v[152:153]
	v_lshl_add_u64 v[6:7], s[6:7], 0, v[6:7]
	v_mov_b32_e32 v8, v0
	v_lshl_add_u64 v[6:7], v[8:9], 1, v[6:7]
	s_or_b64 exec, exec, s[8:9]
	s_add_u32 s8, s19, s10
	s_addc_u32 s9, s20, 0
	global_load_dwordx4 v[112:115], v[6:7], off
	s_lshl_b32 s10, s26, 1
	v_lshlrev_b32_e32 v6, 3, v17
	s_add_u32 s8, s8, s10
	v_and_b32_e32 v6, 56, v6
	s_addc_u32 s9, s9, 0
	v_lshlrev_b32_e32 v6, 1, v6
	v_mov_b32_e32 v7, v1
	v_lshl_add_u64 v[12:13], s[8:9], 0, v[6:7]
	v_ashrrev_i32_e32 v21, 3, v17
	s_movk_i32 s2, 0x2200
	v_mad_i64_i32 v[154:155], s[10:11], v21, s2, v[12:13]
	v_ashrrev_i32_e32 v22, 3, v10
	v_mad_i64_i32 v[156:157], s[10:11], v22, s2, v[12:13]
	global_load_dwordx4 v[116:119], v[154:155], off
	global_load_dwordx4 v[120:123], v[156:157], off
	s_or_b32 s27, s26, 64
	v_add_u32_e32 v12, s27, v18
	v_ashrrev_i32_e32 v13, 31, v12
	s_and_saveexec_b64 s[10:11], vcc
	s_xor_b64 s[10:11], exec, s[10:11]
	v_lshlrev_b64 v[10:11], 6, v[12:13]
	v_lshl_add_u64 v[10:11], s[4:5], 0, v[10:11]
	v_mov_b32_e32 v12, v2
	v_mov_b32_e32 v13, v1
	v_lshl_add_u64 v[10:11], v[12:13], 1, v[10:11]
	v_lshl_add_u64 v[10:11], v[10:11], 0, s[74:75]
	s_andn2_saveexec_b64 s[10:11], s[10:11]
	v_lshlrev_b64 v[10:11], 7, v[12:13]
	v_lshl_add_u64 v[10:11], s[6:7], 0, v[10:11]
	v_lshl_add_u64 v[10:11], v[2:3], 1, v[10:11]
	s_or_b64 exec, exec, s[10:11]
	global_load_dwordx4 v[124:127], v[10:11], off
	v_add_u32_e32 v12, s27, v19
	v_ashrrev_i32_e32 v13, 31, v12
	s_and_saveexec_b64 s[10:11], s[44:45]
	s_xor_b64 s[10:11], exec, s[10:11]
	v_lshlrev_b64 v[10:11], 6, v[12:13]
	v_lshl_add_u64 v[10:11], s[4:5], 0, v[10:11]
	v_mov_b32_e32 v12, v4
	v_mov_b32_e32 v13, v1
	v_lshl_add_u64 v[10:11], v[12:13], 1, v[10:11]
	v_lshl_add_u64 v[10:11], v[10:11], 0, s[74:75]
	s_andn2_saveexec_b64 s[10:11], s[10:11]
	v_lshlrev_b64 v[10:11], 7, v[12:13]
	v_lshl_add_u64 v[10:11], s[6:7], 0, v[10:11]
	v_lshl_add_u64 v[10:11], v[4:5], 1, v[10:11]
	s_or_b64 exec, exec, s[10:11]
	global_load_dwordx4 v[128:131], v[10:11], off
	v_add_u32_e32 v14, s27, v20
	v_ashrrev_i32_e32 v15, 31, v14
	s_and_saveexec_b64 s[10:11], s[46:47]
	s_xor_b64 s[10:11], exec, s[10:11]
	v_lshlrev_b64 v[8:9], 6, v[14:15]
	v_lshl_add_u64 v[8:9], s[4:5], 0, v[8:9]
	v_lshl_add_u64 v[8:9], v[0:1], 1, v[8:9]
	v_lshl_add_u64 v[12:13], v[8:9], 0, s[74:75]
	s_or_saveexec_b64 s[10:11], s[10:11]
	v_mov_b64_e32 v[10:11], v[0:1]
	s_xor_b64 exec, exec, s[10:11]
	v_lshlrev_b64 v[10:11], 7, v[14:15]
	v_lshl_add_u64 v[10:11], s[6:7], 0, v[10:11]
	v_mov_b32_e32 v8, v0
	v_lshl_add_u64 v[12:13], v[8:9], 1, v[10:11]
	v_mov_b64_e32 v[10:11], v[8:9]
	s_or_b64 exec, exec, s[10:11]
	v_mad_i64_i32 v[14:15], s[10:11], v22, s2, 0
	v_mad_i64_i32 v[8:9], s[10:11], v21, s2, 0
	global_load_dwordx4 v[132:135], v[12:13], off
	v_lshl_add_u64 v[12:13], s[8:9], 0, v[14:15]
	v_mov_b32_e32 v7, v1
	s_waitcnt vmcnt(16)
; template <int DK, bool MLA>
; DI void attn_item(const h16* __restrict__ Q, const h16* __restrict__ Kp, const h16* __restrict__ Kr, const h16* __restrict__ Vt,
;                   int kbeg, int kend, h16* __restrict__ out, h16* sm) {
;     ...
;   f32x16 ot[2];
; #pragma unroll
;   for (int i = 0; i < 16; ++i) { ot[0][i] = 0.f; ot[1][i] = 0.f; }
;   float m = -1000.f, lsum = 0.f;
;   u32x4 rkA[NCH], rvA[2], rkB[NCH], rvB[2];
;     ...
;   const int ntile = (kend - kbeg) >> 6;
;   ATT_GLOAD(rkA, rvA, kbeg)
;   ATT_GLOAD(rkB, rvB, kbeg + 64)
;   auto tile = [&](int it, u32x4 (&RK)[NCH], u32x4 (&RV)[2]) {
;     h16* ksm = sm + (it & 1) * BUF;
;     h16* vsm = ksm + 64 * KS;
; #pragma unroll
;     for (int i = 0; i < NCH; ++i) {
;       const int c = tid + 256 * i, key = c / NKC, part = c % NKC;
;       *(u32x4*)(ksm + key * KS + part * 8) = RK[i];
;     }
; #pragma unroll
;     for (int i = 0; i < 2; ++i) {
;       const int c = tid + 256 * i, dv = c >> 3, kc = c & 7;
;       *(u32x4*)(vsm + dv * 72 + kc * 8) = RV[i];
;     }
;     __syncthreads();
;     if (it + 2 < ntile) ATT_GLOAD(RK, RV, kbeg + (it + 2) * 64)
	v_lshl_add_u64 v[158:159], v[12:13], 0, v[6:7]
	v_lshl_add_u64 v[8:9], s[8:9], 0, v[8:9]
	v_lshl_add_u64 v[160:161], v[8:9], 0, v[6:7]
	global_load_dwordx4 v[136:139], v[158:159], off offset:128
	global_load_dwordx4 v[140:143], v[160:161], off offset:128
	s_movk_i32 s2, 0xd0
	v_mul_lo_u32 v7, v18, s2
	s_waitcnt vmcnt(16)
	v_lshl_add_u32 v147, v2, 1, v7
	v_mul_lo_u32 v7, v19, s2
	v_and_b32_e32 v8, 31, v17
	v_lshl_add_u32 v149, v4, 1, v7
	v_mul_lo_u32 v7, v20, s2
	v_lshl_add_u32 v151, v0, 1, v7
	v_lshl_add_u64 v[174:175], v[0:1], 1, s[4:5]
	v_mul_u32_u24_e32 v0, 0x68, v8
	v_lshlrev_b32_e32 v9, 3, v16
	v_mad_u64_u32 v[162:163], s[10:11], v21, s28, v[6:7]
	v_lshlrev_b32_e32 v0, 1, v0
	v_mad_u64_u32 v[164:165], s[10:11], v22, s28, v[6:7]
	v_mov_b32_e32 v6, v2
	v_mov_b32_e32 v7, v1
	v_lshl_add_u64 v[168:169], v[2:3], 1, s[6:7]
	v_mov_b32_e32 v2, v4
	v_mov_b32_e32 v3, v1
	v_lshl_add_u32 v163, v9, 1, v0
	v_mul_u32_u24_e32 v0, 0x48, v8
	v_mov_b32_e32 v14, v1
	v_mov_b32_e32 v15, v1
	s_sub_i32 s8, 0x1100, s26
	v_lshl_add_u64 v[166:167], v[6:7], 1, s[4:5]
	v_lshl_add_u64 v[170:171], v[2:3], 1, s[4:5]
	v_lshl_add_u64 v[172:173], v[4:5], 1, s[6:7]
	v_lshl_add_u64 v[176:177], v[10:11], 1, s[6:7]
	v_lshlrev_b32_e32 v146, 2, v16
	v_lshlrev_b32_e32 v165, 1, v9
	v_lshl_add_u32 v165, v0, 1, v165
	v_mov_b32_e32 v0, v1
	v_mov_b32_e32 v2, v1
	v_mov_b32_e32 v4, v1
	v_mov_b32_e32 v5, v1
	v_mov_b32_e32 v6, v1
	v_mov_b32_e32 v8, v1
	v_mov_b32_e32 v9, v1
	v_mov_b32_e32 v10, v1
	v_mov_b32_e32 v11, v1
	v_mov_b32_e32 v12, v1
	v_mov_b32_e32 v13, v1
	v_mov_b64_e32 v[30:31], v[14:15]
	v_mov_b64_e32 v[46:47], v[14:15]
	v_ashrrev_i32_e32 v145, 31, v144
	s_lshr_b32 s8, s8, 6
	s_mov_b32 s9, 3
	v_mov_b32_e32 v178, 0xc47a0000
	v_mov_b32_e32 v153, 0
	s_movk_i32 s6, 0xc0
	v_mov_b64_e32 v[28:29], v[12:13]
	v_mov_b64_e32 v[26:27], v[10:11]
	v_mov_b64_e32 v[24:25], v[8:9]
	v_mov_b64_e32 v[22:23], v[6:7]
	v_mov_b64_e32 v[20:21], v[4:5]
	v_mov_b64_e32 v[18:19], v[2:3]
	v_mov_b64_e32 v[16:17], v[0:1]
	v_mov_b64_e32 v[44:45], v[12:13]
	v_mov_b64_e32 v[42:43], v[10:11]
	v_mov_b64_e32 v[40:41], v[8:9]
	v_mov_b64_e32 v[38:39], v[6:7]
	v_mov_b64_e32 v[36:37], v[4:5]
	v_mov_b64_e32 v[34:35], v[2:3]
	v_mov_b64_e32 v[32:33], v[0:1]
	v_mov_b32_e32 v204, 0x447a0000
	v_mov_b32_e32 v205, 0x447a0000
	v_mov_b32_e32 v206, 0x447a0000
	v_mov_b32_e32 v207, 0x447a0000
	v_mov_b32_e32 v208, 0x447a0000
	v_mov_b32_e32 v209, 0x447a0000
	v_mov_b32_e32 v210, 0x447a0000
	v_mov_b32_e32 v211, 0x447a0000
	v_mov_b32_e32 v212, 0x447a0000
	v_mov_b32_e32 v213, 0x447a0000
	v_mov_b32_e32 v214, 0x447a0000
	v_mov_b32_e32 v215, 0x447a0000
	v_mov_b32_e32 v216, 0x447a0000
	v_mov_b32_e32 v217, 0x447a0000
	v_mov_b32_e32 v218, 0x447a0000
	v_mov_b32_e32 v219, 0x447a0000
	s_movk_i32 s26, 0x80
	v_add_u32_e32 v2, s26, v148
	v_ashrrev_i32_e32 v3, 31, v2
	v_lshlrev_b64 v[4:5], 7, v[2:3]
	v_lshlrev_b64 v[2:3], 6, v[2:3]
	v_lshl_add_u64 v[2:3], v[166:167], 0, v[2:3]
	v_lshl_add_u64 v[4:5], v[168:169], 0, v[4:5]
	v_lshl_add_u64 v[2:3], v[2:3], 0, s[74:75]
	v_cndmask_b32_e64 v221, v3, v5, s[38:39]
	v_cndmask_b32_e64 v220, v2, v4, s[38:39]
	v_mov_b32_e32 v2, 0x1000
	v_mov_b32_e32 v3, 0x2000
	v_cndmask_b32_e64 v228, v2, v3, s[38:39]
	v_mov_b32_e32 v229, 0
	v_add_u32_e32 v2, s26, v150
	v_ashrrev_i32_e32 v3, 31, v2
	v_lshlrev_b64 v[4:5], 7, v[2:3]
	v_lshlrev_b64 v[2:3], 6, v[2:3]
	v_lshl_add_u64 v[2:3], v[170:171], 0, v[2:3]
	v_lshl_add_u64 v[4:5], v[172:173], 0, v[4:5]
	v_lshl_add_u64 v[2:3], v[2:3], 0, s[74:75]
	v_cndmask_b32_e64 v223, v3, v5, s[40:41]
	v_cndmask_b32_e64 v222, v2, v4, s[40:41]
	v_mov_b32_e32 v2, 0x1000
	v_mov_b32_e32 v3, 0x2000
	v_cndmask_b32_e64 v230, v2, v3, s[40:41]
	v_mov_b32_e32 v231, 0
	v_add_u32_e32 v2, s26, v152
	v_ashrrev_i32_e32 v3, 31, v2
	v_lshlrev_b64 v[4:5], 7, v[2:3]
	v_lshlrev_b64 v[2:3], 6, v[2:3]
	v_lshl_add_u64 v[2:3], v[174:175], 0, v[2:3]
	v_lshl_add_u64 v[4:5], v[176:177], 0, v[4:5]
	v_lshl_add_u64 v[2:3], v[2:3], 0, s[74:75]
	v_cndmask_b32_e64 v227, v3, v5, s[42:43]
	v_cndmask_b32_e64 v226, v2, v4, s[42:43]
	v_mov_b32_e32 v2, 0x1000
	v_mov_b32_e32 v3, 0x2000
	v_cndmask_b32_e64 v232, v2, v3, s[42:43]
	v_mov_b32_e32 v233, 0
	s_branch .LBB0_2771

; #define MFMA(a, b, c) __builtin_amdgcn_mfma_f32_32x32x16_f16((a), (b), (c), 0, 0, 0)
; template <int DK, bool MLA>
; DI void attn_item(const h16* __restrict__ Q, const h16* __restrict__ Kp, const h16* __restrict__ Kr, const h16* __restrict__ Vt,
;                   int kbeg, int kend, h16* __restrict__ out, h16* sm) {
;     ...
;   auto tile = [&](int it, u32x4 (&RK)[NCH], u32x4 (&RV)[2]) {
;     h16* ksm = sm + (it & 1) * BUF;
;     h16* vsm = ksm + 64 * KS;
; #pragma unroll
;     for (int i = 0; i < NCH; ++i) {
;       const int c = tid + 256 * i, key = c / NKC, part = c % NKC;
;       *(u32x4*)(ksm + key * KS + part * 8) = RK[i];
;     }
; #pragma unroll
;     for (int i = 0; i < 2; ++i) {
;       const int c = tid + 256 * i, dv = c >> 3, kc = c & 7;
;       *(u32x4*)(vsm + dv * 72 + kc * 8) = RV[i];
;     }
;     __syncthreads();
;     if (it + 2 < ntile) ATT_GLOAD(RK, RV, kbeg + (it + 2) * 64)
;     f32x16 st[2];
;     const float negm = -m;
; #pragma unroll
;     for (int i = 0; i < 16; ++i) { st[0][i] = negm; st[1][i] = negm; }
; #pragma unroll
;     for (int ks = 0; ks < DK / 16; ++ks) {
;       h16x8 k0 = *(const h16x8*)(ksm + r * KS + ks * 16 + hh * 8);
;       h16x8 k1 = *(const h16x8*)(ksm + (32 + r) * KS + ks * 16 + hh * 8);
;       st[0] = MFMA(k0, qf[ks], st[0]);
;       st[1] = MFMA(k1, qf[ks], st[1]);
;     }
;     float mx = fmaxf(st[0][0], st[1][0]);
; #pragma unroll
;     for (int i = 1; i < 16; ++i) mx = fmaxf(mx, fmaxf(st[0][i], st[1][i]));
;     mx = x32_max(mx);
;     if (__builtin_amdgcn_ballot_w64(mx > 8.f) != 0) {
;       const float dlt = fmaxf(mx, 0.f);
;       const float alpha = __builtin_amdgcn_exp2f(-dlt);
;       m += dlt;
;       lsum *= alpha;
; #pragma unroll
;       for (int i = 0; i < 16; ++i) { ot[0][i] *= alpha; ot[1][i] *= alpha; st[0][i] -= dlt; st[1][i] -= dlt; }
;     }
.LBB0_2771:
	s_add_i32 s10, s9, -1
	s_cmp_ge_u32 s10, s8
	s_waitcnt vmcnt(9)
	ds_write_b128 v147, v[104:107]
	s_waitcnt vmcnt(8)
	ds_write_b128 v149, v[108:111]
	s_waitcnt vmcnt(7)
	ds_write_b128 v151, v[112:115]
	s_waitcnt vmcnt(6)
	ds_write_b128 v162, v[116:119] offset:13312
	s_waitcnt vmcnt(5)
	ds_write_b128 v164, v[120:123] offset:13312
	s_waitcnt lgkmcnt(0)
	s_barrier
	s_cbranch_scc1 .LBB0_2773
	s_sub_i32 s26, s6, 64
	s_ashr_i32 s27, s26, 31
	s_lshl_b64 s[26:27], s[26:27], 1
	global_load_dwordx4 v[104:107], v[220:221], off
	global_load_dwordx4 v[108:111], v[222:223], off
	global_load_dwordx4 v[112:115], v[226:227], off
	v_lshl_add_u64 v[2:3], v[160:161], 0, s[26:27]
	v_lshl_add_u64 v[4:5], v[158:159], 0, s[26:27]
	global_load_dwordx4 v[116:119], v[2:3], off
	global_load_dwordx4 v[120:123], v[4:5], off
	v_lshl_add_u64 v[220:221], v[220:221], 0, v[228:229]
	v_lshl_add_u64 v[222:223], v[222:223], 0, v[230:231]
	v_lshl_add_u64 v[226:227], v[226:227], 0, v[232:233]
.LBB0_2773:
	ds_read_b128 v[2:5], v163
	s_waitcnt lgkmcnt(0)
	s_nop 0
	v_mfma_f32_32x32x16_f16 v[64:79], v[2:5], v[80:83], v[204:219]
	ds_read_b128 v[2:5], v163 offset:6656
	s_waitcnt lgkmcnt(0)
	v_mfma_f32_32x32x16_f16 v[48:63], v[2:5], v[80:83], v[204:219]
	ds_read_b128 v[2:5], v163 offset:32
	s_waitcnt lgkmcnt(0)
	v_mfma_f32_32x32x16_f16 v[64:79], v[2:5], v[84:87], v[64:79]
	ds_read_b128 v[2:5], v163 offset:6688
	s_waitcnt lgkmcnt(0)
	v_mfma_f32_32x32x16_f16 v[48:63], v[2:5], v[84:87], v[48:63]
	ds_read_b128 v[2:5], v163 offset:64
	s_waitcnt lgkmcnt(0)
	v_mfma_f32_32x32x16_f16 v[64:79], v[2:5], v[88:91], v[64:79]
	ds_read_b128 v[2:5], v163 offset:6720
	s_waitcnt lgkmcnt(0)
	v_mfma_f32_32x32x16_f16 v[48:63], v[2:5], v[88:91], v[48:63]
	ds_read_b128 v[2:5], v163 offset:96
	s_waitcnt lgkmcnt(0)
	v_mfma_f32_32x32x16_f16 v[64:79], v[2:5], v[92:95], v[64:79]
	ds_read_b128 v[2:5], v163 offset:6752
	s_waitcnt lgkmcnt(0)
	v_mfma_f32_32x32x16_f16 v[48:63], v[2:5], v[92:95], v[48:63]
	ds_read_b128 v[2:5], v163 offset:128
	s_waitcnt lgkmcnt(0)
	v_mfma_f32_32x32x16_f16 v[64:79], v[2:5], v[96:99], v[64:79]
	ds_read_b128 v[2:5], v163 offset:6784
	s_waitcnt lgkmcnt(0)
	v_mfma_f32_32x32x16_f16 v[48:63], v[2:5], v[96:99], v[48:63]
	ds_read_b128 v[2:5], v163 offset:6816
	s_waitcnt lgkmcnt(0)
	v_mfma_f32_32x32x16_f16 v[48:63], v[2:5], v[100:103], v[48:63]
	ds_read_b128 v[2:5], v163 offset:160
	s_waitcnt lgkmcnt(0)
	v_mfma_f32_32x32x16_f16 v[64:79], v[2:5], v[100:103], v[64:79]
	s_nop 8
	v_max3_f32 v0, v48, v49, v50
	v_max3_f32 v2, v51, v52, v53
	v_max3_f32 v3, v54, v55, v56
	v_max3_f32 v4, v57, v58, v59
	v_max3_f32 v0, v0, v60, v61
	v_max3_f32 v2, v2, v62, v63
	v_max3_f32 v3, v3, v64, v65
	v_max3_f32 v4, v4, v66, v67
	v_max3_f32 v0, v0, v68, v69
	v_max3_f32 v2, v2, v70, v71
	v_max3_f32 v3, v3, v72, v73
	v_max3_f32 v4, v4, v74, v75
	v_max3_f32 v0, v0, v76, v77
	v_max3_f32 v2, v2, v78, v79
	v_max3_f32 v0, v0, v2, v3
	v_max_f32_e32 v0, v0, v4
	v_mov_b32_e32 v2, v0
	s_nop 1
	v_permlane32_swap_b32_e32 v0, v2
	v_max_f32_e32 v0, v0, v2
	v_cmp_lt_f32_e32 vcc, s79, v0
	s_cbranch_vccz .LBB0_2775
	v_max_f32_e32 v0, v0, v0
	v_max_f32_e32 v0, 0, v0
	v_exp_f32_e64 v2, -v0
	v_add_f32_e32 v178, v178, v0
	v_xor_b32_e32 v204, 0x80000000, v178
	v_mov_b32_e32 v205, v204
	v_mov_b32_e32 v206, v204
	v_mov_b32_e32 v207, v204
	v_mov_b32_e32 v208, v204
	v_mov_b32_e32 v209, v204
	v_mov_b32_e32 v210, v204
	v_mov_b32_e32 v211, v204
	v_mov_b32_e32 v212, v204
	v_mov_b32_e32 v213, v204
	v_mov_b32_e32 v214, v204
	v_mov_b32_e32 v215, v204
	v_mov_b32_e32 v216, v204
	v_mov_b32_e32 v217, v204
	v_mov_b32_e32 v218, v204
	v_mov_b32_e32 v219, v204
	v_pk_add_f32 v[64:65], v[64:65], v[0:1] op_sel_hi:[1,0] neg_lo:[0,1] neg_hi:[0,1]
	v_pk_add_f32 v[48:49], v[48:49], v[0:1] op_sel_hi:[1,0] neg_lo:[0,1] neg_hi:[0,1]
	v_mul_f32_e32 v153, v153, v2
	v_pk_add_f32 v[66:67], v[66:67], v[0:1] op_sel_hi:[1,0] neg_lo:[0,1] neg_hi:[0,1]
	v_pk_add_f32 v[50:51], v[50:51], v[0:1] op_sel_hi:[1,0] neg_lo:[0,1] neg_hi:[0,1]
	v_pk_add_f32 v[68:69], v[68:69], v[0:1] op_sel_hi:[1,0] neg_lo:[0,1] neg_hi:[0,1]
	v_pk_add_f32 v[52:53], v[52:53], v[0:1] op_sel_hi:[1,0] neg_lo:[0,1] neg_hi:[0,1]
	v_pk_add_f32 v[70:71], v[70:71], v[0:1] op_sel_hi:[1,0] neg_lo:[0,1] neg_hi:[0,1]
	v_pk_add_f32 v[54:55], v[54:55], v[0:1] op_sel_hi:[1,0] neg_lo:[0,1] neg_hi:[0,1]
	v_pk_add_f32 v[72:73], v[72:73], v[0:1] op_sel_hi:[1,0] neg_lo:[0,1] neg_hi:[0,1]
	v_pk_add_f32 v[56:57], v[56:57], v[0:1] op_sel_hi:[1,0] neg_lo:[0,1] neg_hi:[0,1]
	v_pk_add_f32 v[74:75], v[74:75], v[0:1] op_sel_hi:[1,0] neg_lo:[0,1] neg_hi:[0,1]
	v_pk_add_f32 v[58:59], v[58:59], v[0:1] op_sel_hi:[1,0] neg_lo:[0,1] neg_hi:[0,1]
	v_pk_add_f32 v[76:77], v[76:77], v[0:1] op_sel_hi:[1,0] neg_lo:[0,1] neg_hi:[0,1]
	v_pk_add_f32 v[60:61], v[60:61], v[0:1] op_sel_hi:[1,0] neg_lo:[0,1] neg_hi:[0,1]
	v_pk_mul_f32 v[46:47], v[46:47], v[2:3] op_sel_hi:[1,0]
	v_pk_mul_f32 v[44:45], v[44:45], v[2:3] op_sel_hi:[1,0]
	v_pk_mul_f32 v[42:43], v[42:43], v[2:3] op_sel_hi:[1,0]
	v_pk_mul_f32 v[40:41], v[40:41], v[2:3] op_sel_hi:[1,0]
	v_pk_mul_f32 v[38:39], v[38:39], v[2:3] op_sel_hi:[1,0]
	v_pk_mul_f32 v[36:37], v[36:37], v[2:3] op_sel_hi:[1,0]
	v_pk_mul_f32 v[34:35], v[34:35], v[2:3] op_sel_hi:[1,0]
	v_pk_mul_f32 v[32:33], v[32:33], v[2:3] op_sel_hi:[1,0]
	v_pk_mul_f32 v[30:31], v[30:31], v[2:3] op_sel_hi:[1,0]
	v_pk_mul_f32 v[28:29], v[28:29], v[2:3] op_sel_hi:[1,0]
	v_pk_mul_f32 v[26:27], v[26:27], v[2:3] op_sel_hi:[1,0]
	v_pk_mul_f32 v[24:25], v[24:25], v[2:3] op_sel_hi:[1,0]
	v_pk_mul_f32 v[22:23], v[22:23], v[2:3] op_sel_hi:[1,0]
	v_pk_mul_f32 v[20:21], v[20:21], v[2:3] op_sel_hi:[1,0]
	v_pk_mul_f32 v[18:19], v[18:19], v[2:3] op_sel_hi:[1,0]
	v_pk_mul_f32 v[16:17], v[16:17], v[2:3] op_sel_hi:[1,0]
	v_pk_add_f32 v[78:79], v[78:79], v[0:1] op_sel_hi:[1,0] neg_lo:[0,1] neg_hi:[0,1]
	v_pk_add_f32 v[62:63], v[62:63], v[0:1] op_sel_hi:[1,0] neg_lo:[0,1] neg_hi:[0,1]
; #define MFMA(a, b, c) __builtin_amdgcn_mfma_f32_32x32x16_f16((a), (b), (c), 0, 0, 0)
; template <int DK, bool MLA>
; DI void attn_item(const h16* __restrict__ Q, const h16* __restrict__ Kp, const h16* __restrict__ Kr, const h16* __restrict__ Vt,
;                   int kbeg, int kend, h16* __restrict__ out, h16* sm) {
;     ...
; #pragma unroll
;     for (int i = 0; i < NCH; ++i) {
;       const int c = tid + 256 * i, key = c / NKC, part = c % NKC;
;       *(u32x4*)(ksm + key * KS + part * 8) = RK[i];
;     }
; #pragma unroll
;     for (int i = 0; i < 2; ++i) {
;       const int c = tid + 256 * i, dv = c >> 3, kc = c & 7;
;       *(u32x4*)(vsm + dv * 72 + kc * 8) = RV[i];
;     }
;     __syncthreads();
;     if (it + 2 < ntile) ATT_GLOAD(RK, RV, kbeg + (it + 2) * 64)
;     ...
;     float ps = 0.f;
; #pragma unroll
;     for (int i = 0; i < 16; ++i) {
;       st[0][i] = __builtin_amdgcn_exp2f(st[0][i]);
;       st[1][i] = __builtin_amdgcn_exp2f(st[1][i]);
;       ps += st[0][i] + st[1][i];
;     }
;     lsum += ps;
; #pragma unroll
;     for (int s4 = 0; s4 < 4; ++s4) {
;       const int kt2 = s4 >> 1, hf = s4 & 1;
;       h16x8 pb;
; #pragma unroll
;       for (int j = 0; j < 8; ++j) pb[j] = (h16)st[kt2][8 * hf + j];
;       const int kb = kt2 * 32 + 16 * hf;
; #pragma unroll
;       for (int dt = 0; dt < 2; ++dt) {
;         const h16* vp = vsm + (dt * 32 + r) * 72 + kb + 4 * hh;
;         h16x4 lo = *(const h16x4*)vp, hi = *(const h16x4*)(vp + 8);
;         h16x8 va = __builtin_shufflevector(lo, hi, 0, 1, 2, 3, 4, 5, 6, 7);
;         ot[dt] = MFMA(va, pb, ot[dt]);
;       }
;     }
.LBB0_2775:
	v_exp_f32_e32 v192, v64
	v_exp_f32_e32 v193, v65
	v_exp_f32_e32 v5, v66
	v_exp_f32_e32 v6, v67
	v_exp_f32_e32 v186, v68
	v_exp_f32_e32 v9, v69
	v_exp_f32_e32 v188, v70
	v_exp_f32_e32 v189, v71
	v_exp_f32_e32 v15, v60
	v_add_u32_e32 v60, 0x3000, v165
	v_exp_f32_e32 v187, v52
	v_exp_f32_e32 v13, v53
	v_exp_f32_e32 v190, v54
	v_exp_f32_e32 v191, v55
	v_exp_f32_e32 v183, v56
	v_exp_f32_e32 v184, v57
	v_exp_f32_e32 v185, v58
	v_exp_f32_e32 v14, v59
	ds_read_b128 v[52:55], v60 offset:1024
	ds_read_b128 v[56:59], v60 offset:1056
	v_exp_f32_e32 v194, v48
	v_exp_f32_e32 v195, v49
	v_exp_f32_e32 v7, v50
	v_exp_f32_e32 v8, v51
	v_exp_f32_e32 v179, v61
	v_cvt_pk_f16_f32 v51, v188, v189
	v_cvt_pk_f16_f32 v50, v186, v9
	v_cvt_pk_f16_f32 v49, v5, v6
	v_cvt_pk_f16_f32 v48, v192, v193
	v_add_u32_e32 v61, 0x4000, v165
	v_exp_f32_e32 v180, v72
	s_waitcnt lgkmcnt(1)
	v_mfma_f32_32x32x16_f16 v[32:47], v[52:55], v[48:51], v[32:47]
	ds_read_b128 v[52:55], v61 offset:1536
	v_exp_f32_e32 v181, v73
	v_exp_f32_e32 v182, v74
	v_exp_f32_e32 v10, v75
	v_exp_f32_e32 v11, v76
	v_exp_f32_e32 v12, v77
	v_exp_f32_e32 v0, v78
	s_waitcnt lgkmcnt(0)
	v_mfma_f32_32x32x16_f16 v[16:31], v[52:55], v[48:51], v[16:31]
	ds_read_b128 v[52:55], v61 offset:1568
	v_exp_f32_e32 v2, v79
	v_cvt_pk_f16_f32 v50, v11, v12
	v_cvt_pk_f16_f32 v49, v182, v10
	v_cvt_pk_f16_f32 v48, v180, v181
	v_cvt_pk_f16_f32 v51, v0, v2
	v_exp_f32_e32 v3, v62
	v_exp_f32_e32 v4, v63
	s_waitcnt lgkmcnt(0)
	v_mfma_f32_32x32x16_f16 v[16:31], v[52:55], v[48:51], v[16:31]
	ds_read_b128 v[52:55], v60 offset:1088
	s_cmp_ge_u32 s9, s8
	v_mfma_f32_32x32x16_f16 v[32:47], v[56:59], v[48:51], v[32:47]
	v_cvt_pk_f16_f32 v51, v190, v191
	v_cvt_pk_f16_f32 v50, v187, v13
	v_cvt_pk_f16_f32 v49, v7, v8
	v_cvt_pk_f16_f32 v48, v194, v195
	s_waitcnt lgkmcnt(0)
	s_nop 0
	v_mfma_f32_32x32x16_f16 v[32:47], v[52:55], v[48:51], v[32:47]
	ds_read_b128 v[52:55], v61 offset:1600
	s_waitcnt lgkmcnt(0)
	v_mfma_f32_32x32x16_f16 v[16:31], v[52:55], v[48:51], v[16:31]
	ds_read_b128 v[52:55], v60 offset:1120
	v_cvt_pk_f16_f32 v51, v3, v4
	v_cvt_pk_f16_f32 v50, v15, v179
	v_cvt_pk_f16_f32 v49, v185, v14
	v_cvt_pk_f16_f32 v48, v183, v184
	s_waitcnt lgkmcnt(0)
	s_nop 0
	v_mfma_f32_32x32x16_f16 v[32:47], v[52:55], v[48:51], v[32:47]
	ds_read_b128 v[52:55], v61 offset:1632
	s_waitcnt vmcnt(4)
	ds_write_b128 v147, v[124:127] offset:22528
	s_waitcnt vmcnt(3)
	ds_write_b128 v149, v[128:131] offset:22528
	s_waitcnt vmcnt(2)
	ds_write_b128 v151, v[132:135] offset:22528
	s_waitcnt vmcnt(0)
	ds_write_b128 v162, v[140:143] offset:35840
	ds_write_b128 v164, v[136:139] offset:35840
	s_waitcnt lgkmcnt(0)
	s_barrier
	v_mfma_f32_32x32x16_f16 v[16:31], v[52:55], v[48:51], v[16:31]
	s_cbranch_scc1 .LBB0_2777
	s_ashr_i32 s7, s6, 31
	s_lshl_b64 s[26:27], s[6:7], 1
	global_load_dwordx4 v[124:127], v[220:221], off
	global_load_dwordx4 v[128:131], v[222:223], off
	global_load_dwordx4 v[132:135], v[226:227], off
	v_lshl_add_u64 v[48:49], v[154:155], 0, s[26:27]
	v_lshl_add_u64 v[50:51], v[156:157], 0, s[26:27]
	global_load_dwordx4 v[140:143], v[48:49], off
	global_load_dwordx4 v[136:139], v[50:51], off
	v_lshl_add_u64 v[220:221], v[220:221], 0, v[228:229]
	v_lshl_add_u64 v[222:223], v[222:223], 0, v[230:231]
	v_lshl_add_u64 v[226:227], v[226:227], 0, v[232:233]
; #define MFMA(a, b, c) __builtin_amdgcn_mfma_f32_32x32x16_f16((a), (b), (c), 0, 0, 0)
; template <int DK, bool MLA>
; DI void attn_item(const h16* __restrict__ Q, const h16* __restrict__ Kp, const h16* __restrict__ Kr, const h16* __restrict__ Vt,
;                   int kbeg, int kend, h16* __restrict__ out, h16* sm) {
;     ...
;     f32x16 st[2];
;     const float negm = -m;
; #pragma unroll
;     for (int i = 0; i < 16; ++i) { st[0][i] = negm; st[1][i] = negm; }
; #pragma unroll
;     for (int ks = 0; ks < DK / 16; ++ks) {
;       h16x8 k0 = *(const h16x8*)(ksm + r * KS + ks * 16 + hh * 8);
;       h16x8 k1 = *(const h16x8*)(ksm + (32 + r) * KS + ks * 16 + hh * 8);
;       st[0] = MFMA(k0, qf[ks], st[0]);
;       st[1] = MFMA(k1, qf[ks], st[1]);
;     }
;     float mx = fmaxf(st[0][0], st[1][0]);
; #pragma unroll
;     for (int i = 1; i < 16; ++i) mx = fmaxf(mx, fmaxf(st[0][i], st[1][i]));
;     mx = x32_max(mx);
;     if (__builtin_amdgcn_ballot_w64(mx > 8.f) != 0) {
;       const float dlt = fmaxf(mx, 0.f);
;       const float alpha = __builtin_amdgcn_exp2f(-dlt);
;       m += dlt;
;       lsum *= alpha;
; #pragma unroll
;       for (int i = 0; i < 16; ++i) { ot[0][i] *= alpha; ot[1][i] *= alpha; st[0][i] -= dlt; st[1][i] -= dlt; }
;     }
.LBB0_2777:
	ds_read_b128 v[196:199], v163 offset:22528
	v_add_f32_e32 v192, v194, v192
	v_add_f32_e32 v200, 0, v192
	v_add_f32_e32 v201, v195, v193
	ds_read_b128 v[192:195], v163 offset:29280
	s_waitcnt lgkmcnt(1)
	v_mfma_f32_32x32x16_f16 v[64:79], v[196:199], v[80:83], v[204:219]
	ds_read_b128 v[196:199], v163 offset:29184
	v_add_f32_e32 v5, v7, v5
	v_add_f32_e32 v6, v8, v6
	v_add_f32_e32 v0, v3, v0
	v_add_f32_e32 v2, v4, v2
	s_waitcnt lgkmcnt(0)
	v_mfma_f32_32x32x16_f16 v[48:63], v[196:199], v[80:83], v[204:219]
	ds_read_b128 v[196:199], v163 offset:22560
	s_waitcnt lgkmcnt(0)
	v_mfma_f32_32x32x16_f16 v[64:79], v[196:199], v[84:87], v[64:79]
	ds_read_b128 v[196:199], v163 offset:29216
	s_waitcnt lgkmcnt(0)
	v_mfma_f32_32x32x16_f16 v[48:63], v[196:199], v[84:87], v[48:63]
	ds_read_b128 v[196:199], v163 offset:22592
	s_waitcnt lgkmcnt(0)
	v_mfma_f32_32x32x16_f16 v[64:79], v[196:199], v[88:91], v[64:79]
	ds_read_b128 v[196:199], v163 offset:29248
	s_waitcnt lgkmcnt(0)
	v_mfma_f32_32x32x16_f16 v[48:63], v[196:199], v[88:91], v[48:63]
	ds_read_b128 v[196:199], v163 offset:22624
	s_waitcnt lgkmcnt(0)
	v_mfma_f32_32x32x16_f16 v[64:79], v[196:199], v[92:95], v[64:79]
	v_add_f32_e32 v196, v201, v200
	v_add_f32_e32 v5, v5, v196
	v_add_f32_e32 v5, v6, v5
	v_add_f32_e32 v6, v187, v186
	v_add_f32_e32 v5, v6, v5
	v_add_f32_e32 v6, v13, v9
	v_add_f32_e32 v5, v6, v5
	v_add_f32_e32 v6, v190, v188
	v_add_f32_e32 v5, v6, v5
	ds_read_b128 v[6:9], v163 offset:29312
	v_mfma_f32_32x32x16_f16 v[48:63], v[192:195], v[92:95], v[48:63]
	ds_read_b128 v[196:199], v163 offset:22656
	v_add_f32_e32 v13, v191, v189
	v_add_f32_e32 v5, v13, v5
	v_add_f32_e32 v13, v183, v180
	v_add_f32_e32 v5, v13, v5
	v_add_f32_e32 v13, v184, v181
	v_add_f32_e32 v5, v13, v5
	v_add_f32_e32 v13, v185, v182
	ds_read_b128 v[180:183], v163 offset:29344
	s_waitcnt lgkmcnt(2)
	v_mfma_f32_32x32x16_f16 v[48:63], v[6:9], v[96:99], v[48:63]
	v_add_f32_e32 v5, v13, v5
	v_add_f32_e32 v6, v14, v10
	v_add_f32_e32 v5, v6, v5
	v_add_f32_e32 v6, v15, v11
	v_add_f32_e32 v5, v6, v5
	ds_read_b128 v[6:9], v163 offset:22688
	v_add_f32_e32 v10, v179, v12
	s_waitcnt lgkmcnt(2)
	v_mfma_f32_32x32x16_f16 v[64:79], v[196:199], v[96:99], v[64:79]
	v_add_f32_e32 v5, v10, v5
	v_add_f32_e32 v0, v0, v5
	v_add_f32_e32 v0, v2, v0
	v_add_f32_e32 v0, v153, v0
	s_waitcnt lgkmcnt(1)
	v_mfma_f32_32x32x16_f16 v[48:63], v[180:183], v[100:103], v[48:63]
	s_waitcnt lgkmcnt(0)
	v_mfma_f32_32x32x16_f16 v[64:79], v[6:9], v[100:103], v[64:79]
	s_nop 9
	v_max3_f32 v2, v48, v49, v50
	v_max3_f32 v3, v51, v52, v53
	v_max3_f32 v4, v54, v55, v56
	v_max3_f32 v5, v57, v58, v59
	v_max3_f32 v2, v2, v60, v61
	v_max3_f32 v3, v3, v62, v63
	v_max3_f32 v4, v4, v64, v65
	v_max3_f32 v5, v5, v66, v67
	v_max3_f32 v2, v2, v68, v69
	v_max3_f32 v3, v3, v70, v71
	v_max3_f32 v4, v4, v72, v73
	v_max3_f32 v5, v5, v74, v75
	v_max3_f32 v2, v2, v76, v77
	v_max3_f32 v3, v3, v78, v79
	v_max3_f32 v2, v2, v3, v4
	v_max_f32_e32 v2, v2, v5
	v_mov_b32_e32 v3, v2
	s_nop 1
	v_permlane32_swap_b32_e32 v2, v3
	v_max_f32_e32 v2, v2, v3
	v_cmp_lt_f32_e32 vcc, s79, v2
	s_cbranch_vccz .LBB0_2770
	v_max_f32_e32 v2, v2, v2
	v_max_f32_e32 v2, 0, v2
	v_exp_f32_e64 v4, -v2
	v_add_f32_e32 v178, v178, v2
	v_xor_b32_e32 v204, 0x80000000, v178
	v_mov_b32_e32 v205, v204
	v_mov_b32_e32 v206, v204
	v_mov_b32_e32 v207, v204
	v_mov_b32_e32 v208, v204
	v_mov_b32_e32 v209, v204
	v_mov_b32_e32 v210, v204
	v_mov_b32_e32 v211, v204
	v_mov_b32_e32 v212, v204
	v_mov_b32_e32 v213, v204
	v_mov_b32_e32 v214, v204
	v_mov_b32_e32 v215, v204
	v_mov_b32_e32 v216, v204
	v_mov_b32_e32 v217, v204
	v_mov_b32_e32 v218, v204
	v_mov_b32_e32 v219, v204
	v_pk_add_f32 v[64:65], v[64:65], v[2:3] op_sel_hi:[1,0] neg_lo:[0,1] neg_hi:[0,1]
	v_pk_add_f32 v[48:49], v[48:49], v[2:3] op_sel_hi:[1,0] neg_lo:[0,1] neg_hi:[0,1]
	v_mul_f32_e32 v0, v0, v4
	v_pk_add_f32 v[66:67], v[66:67], v[2:3] op_sel_hi:[1,0] neg_lo:[0,1] neg_hi:[0,1]
	v_pk_add_f32 v[50:51], v[50:51], v[2:3] op_sel_hi:[1,0] neg_lo:[0,1] neg_hi:[0,1]
	v_pk_add_f32 v[68:69], v[68:69], v[2:3] op_sel_hi:[1,0] neg_lo:[0,1] neg_hi:[0,1]
	v_pk_add_f32 v[52:53], v[52:53], v[2:3] op_sel_hi:[1,0] neg_lo:[0,1] neg_hi:[0,1]
	v_pk_add_f32 v[70:71], v[70:71], v[2:3] op_sel_hi:[1,0] neg_lo:[0,1] neg_hi:[0,1]
	v_pk_add_f32 v[54:55], v[54:55], v[2:3] op_sel_hi:[1,0] neg_lo:[0,1] neg_hi:[0,1]
	v_pk_add_f32 v[72:73], v[72:73], v[2:3] op_sel_hi:[1,0] neg_lo:[0,1] neg_hi:[0,1]
	v_pk_add_f32 v[56:57], v[56:57], v[2:3] op_sel_hi:[1,0] neg_lo:[0,1] neg_hi:[0,1]
	v_pk_add_f32 v[74:75], v[74:75], v[2:3] op_sel_hi:[1,0] neg_lo:[0,1] neg_hi:[0,1]
	v_pk_add_f32 v[58:59], v[58:59], v[2:3] op_sel_hi:[1,0] neg_lo:[0,1] neg_hi:[0,1]
	v_pk_add_f32 v[76:77], v[76:77], v[2:3] op_sel_hi:[1,0] neg_lo:[0,1] neg_hi:[0,1]
	v_pk_add_f32 v[60:61], v[60:61], v[2:3] op_sel_hi:[1,0] neg_lo:[0,1] neg_hi:[0,1]
	v_pk_mul_f32 v[46:47], v[46:47], v[4:5] op_sel_hi:[1,0]
	v_pk_mul_f32 v[44:45], v[44:45], v[4:5] op_sel_hi:[1,0]
	v_pk_mul_f32 v[42:43], v[42:43], v[4:5] op_sel_hi:[1,0]
	v_pk_mul_f32 v[40:41], v[40:41], v[4:5] op_sel_hi:[1,0]
	v_pk_mul_f32 v[38:39], v[38:39], v[4:5] op_sel_hi:[1,0]
	v_pk_mul_f32 v[36:37], v[36:37], v[4:5] op_sel_hi:[1,0]
	v_pk_mul_f32 v[34:35], v[34:35], v[4:5] op_sel_hi:[1,0]
	v_pk_mul_f32 v[32:33], v[32:33], v[4:5] op_sel_hi:[1,0]
	v_pk_mul_f32 v[30:31], v[30:31], v[4:5] op_sel_hi:[1,0]
	v_pk_mul_f32 v[28:29], v[28:29], v[4:5] op_sel_hi:[1,0]
	v_pk_mul_f32 v[26:27], v[26:27], v[4:5] op_sel_hi:[1,0]
	v_pk_mul_f32 v[24:25], v[24:25], v[4:5] op_sel_hi:[1,0]
	v_pk_mul_f32 v[22:23], v[22:23], v[4:5] op_sel_hi:[1,0]
	v_pk_mul_f32 v[20:21], v[20:21], v[4:5] op_sel_hi:[1,0]
	v_pk_mul_f32 v[18:19], v[18:19], v[4:5] op_sel_hi:[1,0]
	v_pk_mul_f32 v[16:17], v[16:17], v[4:5] op_sel_hi:[1,0]
	v_pk_add_f32 v[78:79], v[78:79], v[2:3] op_sel_hi:[1,0] neg_lo:[0,1] neg_hi:[0,1]
	v_pk_add_f32 v[62:63], v[62:63], v[2:3] op_sel_hi:[1,0] neg_lo:[0,1] neg_hi:[0,1]
	s_branch .LBB0_2770
